# grid barrier flag polling without s_sleep back-off (tight poll) on top of opt26
# speedup vs baseline: 1.0025x; 1.0009x over previous
; __device__ __forceinline__ void grid_barrier(unsigned* bar, unsigned k) {
;     ...
;         const unsigned old = __hip_atomic_fetch_add(bar + 64 * g, 1u, __ATOMIC_RELAXED, __HIP_MEMORY_SCOPE_AGENT);
;         if (old == k * gsz - 1u) {
;             const unsigned old2 = __hip_atomic_fetch_add(bar + 64 * 32, 1u, __ATOMIC_RELAXED, __HIP_MEMORY_SCOPE_AGENT);
;             if (old2 == k * ng - 1u) for (unsigned j = 0; j < ng; ++j) __hip_atomic_store(bar + 64 * (64 + j), k, __ATOMIC_RELAXED, __HIP_MEMORY_SCOPE_AGENT);
;         }
;         while (__hip_atomic_load(bar + 64 * (64 + g), __ATOMIC_RELAXED, __HIP_MEMORY_SCOPE_AGENT) < k) __builtin_amdgcn_s_sleep(2);
;         __builtin_amdgcn_fence(__ATOMIC_ACQUIRE, "agent");
;         asm volatile("s_waitcnt vmcnt(0)" ::: "memory");
.LBB0_27:
	s_nop 0
	global_load_dword v0, v147, s[2:3] sc1
	s_waitcnt vmcnt(0)
	v_cmp_gt_u32_e32 vcc, s70, v0
	s_cbranch_vccnz .LBB0_27

; __device__ __forceinline__ void grid_barrier(unsigned* bar, unsigned k) {
;     ...
;         const unsigned old = __hip_atomic_fetch_add(bar + 64 * g, 1u, __ATOMIC_RELAXED, __HIP_MEMORY_SCOPE_AGENT);
;         if (old == k * gsz - 1u) {
;             const unsigned old2 = __hip_atomic_fetch_add(bar + 64 * 32, 1u, __ATOMIC_RELAXED, __HIP_MEMORY_SCOPE_AGENT);
;             if (old2 == k * ng - 1u) for (unsigned j = 0; j < ng; ++j) __hip_atomic_store(bar + 64 * (64 + j), k, __ATOMIC_RELAXED, __HIP_MEMORY_SCOPE_AGENT);
;         }
;         while (__hip_atomic_load(bar + 64 * (64 + g), __ATOMIC_RELAXED, __HIP_MEMORY_SCOPE_AGENT) < k) __builtin_amdgcn_s_sleep(2);
;         __builtin_amdgcn_fence(__ATOMIC_ACQUIRE, "agent");
;         asm volatile("s_waitcnt vmcnt(0)" ::: "memory");
.LBB0_190:
	s_nop 0
	global_load_dword v0, v147, s[2:3] sc1
	s_waitcnt vmcnt(0)
	v_cmp_gt_u32_e32 vcc, s30, v0
	s_cbranch_vccnz .LBB0_190
